# mem_attn: next round's K/Q/V loads issued before PV; sample rows one wave per workgroup over 128 workgroups
# speedup vs baseline: 1.0160x; 1.0002x over previous
; #define LAS __attribute__((address_space(3)))
; __device__ __forceinline__ int opaque_tid(int wv) { int t = wv * 64 + (int)__builtin_amdgcn_mbcnt_hi(~0u, __builtin_amdgcn_mbcnt_lo(~0u, 0u)); asm volatile("" : "+v"(t)); return t; }
; __device__ __forceinline__ void mem_attn_phase(int wv, const Args& A, LAS unsigned char* lds, int G) {
;     const int tid = opaque_tid(wv), lane = tid & 63, w = tid >> 6, fr = lane & 15, fq = lane >> 4;
;     unsigned char* ws = A.ws;
;     const h16* MQ = (const h16*)(ws + WS_MQ); h16* MO = (h16*)(ws + WS_MO);
;     LAS h16* Pw = (LAS h16*)(lds + w * 8448);
;     for (int wu = blockIdx.x * 8 + w; wu < (MT / 16) * 4; wu += G * 8) {
;         const int blk = wu >> 3; const int h = blk & 3, tile = (blk >> 2) * 8 + (wu & 7); const size_t row0 = (size_t)tile * 16;
;         const h16* Kb; const h16* VTb;
;         if (row0 < NP) { const int b = (int)(row0 >> 14); Kb = (const h16*)(ws + WS_MK16) + (size_t)b * 256 * 512; VTb = (const h16*)(ws + WS_MVT) + (size_t)(b * 4 + h) * 32768; }
;         else { const int bs = (int)((row0 - NP) >> 6); Kb = (const h16*)(ws + WS_CMK) + (size_t)bs * 256 * 512; VTb = (const h16*)(ws + WS_CMVT) + (size_t)(bs * 4 + h) * 32768; }
;         h16x8 qf[4];
; #pragma unroll
;         for (int ks = 0; ks < 4; ++ks) qf[ks] = __builtin_bit_cast(h16x8, *(const u32x4*)(MQ + (row0 + fr) * 512 + h * 128 + ks * 32 + fq * 8));
;         f32x4 lg[16]; float m = -INFINITY;
; #pragma unroll
;         for (int kt = 0; kt < 16; ++kt) { f32x4 a = {0.f, 0.f, 0.f, 0.f};
; #pragma unroll
;             for (int ks = 0; ks < 4; ++ks) { const h16x8 kf = __builtin_bit_cast(h16x8, *(const u32x4*)(Kb + (size_t)(kt * 16 + fr) * 512 + h * 128 + ks * 32 + fq * 8)); a = __builtin_amdgcn_mfma_f32_16x16x32_f16(kf, qf[ks], a, 0, 0, 0); }
;             lg[kt] = a; m = fmaxf(m, fmaxf(fmaxf(a[0], a[1]), fmaxf(a[2], a[3]))); }
.LBB0_2399:
	s_or_b64 exec, exec, s[6:7]
	s_waitcnt lgkmcnt(0)
	v_mov_b32_e32 v0, v170
	s_barrier
	v_mbcnt_lo_u32_b32 v0, -1, 0
	v_mbcnt_hi_u32_b32 v0, -1, v0
	v_and_b32_e32 v1, 15, v0
	v_lshrrev_b32_e32 v2, 4, v0
	v_ashrrev_i32_e32 v64, 6, v170
	s_nop 0
	v_readfirstlane_b32 s70, v64
	v_lshlrev_b32_e32 v4, 10, v1
	v_lshl_add_u32 v4, v2, 4, v4
	v_lshlrev_b32_e32 v5, 9, v1
	v_lshl_add_u32 v5, v2, 4, v5
	v_lshlrev_b32_e32 v7, 4, v0
	v_add_u32_e32 v7, 0x11000, v7
	s_lshl_b32 s32, s70, 13
	v_add_u32_e32 v6, s32, v7
	s_mul_i32 s32, s70, 0x2100
	v_mul_u32_u24_e32 v8, 0x210, v1
	v_add_u32_e32 v8, s32, v8
	v_lshl_add_u32 v9, v2, 4, v8
	v_lshl_add_u32 v8, v2, 3, v8
	v_lshlrev_b32_e32 v10, 10, v1
	v_lshl_add_u32 v10, v2, 3, v10
	v_xor_b32_e32 v11, 16, v0
	v_lshlrev_b32_e32 v11, 2, v11
	v_xor_b32_e32 v12, 32, v0
	v_lshlrev_b32_e32 v12, 2, v12
	s_mov_b32 s71, 0
	s_lshl_b32 s72, s71, 8
	s_add_i32 s73, s2, s72
	s_and_b32 s74, s73, 3
	s_lshr_b32 s75, s73, 2
	s_lshl_b32 s75, s75, 3
	s_add_i32 s75, s75, s70
	s_lshr_b32 s76, s75, 10
	s_lshl_b32 s32, s76, 18
	s_lshl_b32 s33, s74, 8
	s_add_i32 s32, s32, s33
	s_lshl_b32 s33, s70, 15
	s_add_i32 s32, s32, s33
	s_add_u32 s78, s44, 0x3cc4d000
	s_addc_u32 s79, s45, 0
	s_add_u32 s78, s78, s32
	s_addc_u32 s79, s79, 0
	s_add_u32 s88, s78, 0x4000
	s_addc_u32 s89, s79, 0
	s_lshl_b32 s32, s76, 2
	s_add_i32 s32, s32, s74
	s_lshl_b32 s32, s32, 16
	s_lshl_b32 s33, s70, 13
	s_add_i32 s32, s32, s33
	s_add_u32 s90, s44, 0x3cccd000
	s_addc_u32 s91, s45, 0
	s_add_u32 s90, s90, s32
	s_addc_u32 s91, s91, 0
	s_lshl_b32 s32, s75, 14
	s_lshl_b32 s33, s74, 8
	s_add_i32 s32, s32, s33
	s_add_u32 s92, s44, 0x324c1000
	s_addc_u32 s93, s45, 0
	s_add_u32 s92, s92, s32
	s_addc_u32 s93, s93, 0
	s_add_u32 s36, s44, 0x34541000
	s_addc_u32 s37, s45, 0
	s_add_u32 s36, s36, s32
	s_addc_u32 s37, s37, 0
	global_load_dwordx4 v[140:143], v4, s[78:79]
	global_load_dwordx4 v[144:147], v4, s[78:79] offset:64
	global_load_dwordx4 v[148:151], v4, s[78:79] offset:128
	global_load_dwordx4 v[152:155], v4, s[78:79] offset:192
	global_load_dwordx4 v[156:159], v4, s[88:89]
	global_load_dwordx4 v[160:163], v4, s[88:89] offset:64
	global_load_dwordx4 v[164:167], v4, s[88:89] offset:128
	global_load_dwordx4 v[214:217], v4, s[88:89] offset:192
	global_load_dwordx4 v[16:19], v4, s[92:93]
	global_load_dwordx4 v[20:23], v4, s[92:93] offset:64
	global_load_dwordx4 v[24:27], v4, s[92:93] offset:128
	global_load_dwordx4 v[28:31], v4, s[92:93] offset:192
	global_load_dwordx4 v[182:185], v5, s[90:91]
	global_load_dwordx4 v[186:189], v5, s[90:91] offset:64
	global_load_dwordx4 v[190:193], v5, s[90:91] offset:128
	global_load_dwordx4 v[194:197], v5, s[90:91] offset:192
	global_load_dwordx4 v[198:201], v5, s[90:91] offset:256
	global_load_dwordx4 v[202:205], v5, s[90:91] offset:320
	global_load_dwordx4 v[206:209], v5, s[90:91] offset:384
	global_load_dwordx4 v[210:213], v5, s[90:91] offset:448
	s_waitcnt vmcnt(19)
	ds_write_b128 v6, v[140:143]
	s_waitcnt vmcnt(18)
	ds_write_b128 v6, v[144:147] offset:1024
	s_waitcnt vmcnt(17)
	ds_write_b128 v6, v[148:151] offset:2048
	s_waitcnt vmcnt(16)
	ds_write_b128 v6, v[152:155] offset:3072
	s_waitcnt vmcnt(15)
	ds_write_b128 v6, v[156:159] offset:4096
	s_waitcnt vmcnt(14)
	ds_write_b128 v6, v[160:163] offset:5120
	s_waitcnt vmcnt(13)
	ds_write_b128 v6, v[164:167] offset:6144
	s_waitcnt vmcnt(12)
	ds_write_b128 v6, v[214:217] offset:7168
	s_branch .Lma_staged
.Lma_round:
	s_barrier
	s_waitcnt vmcnt(27)
	ds_write_b128 v6, v[140:143]
	s_waitcnt vmcnt(26)
	ds_write_b128 v6, v[144:147] offset:1024
	s_waitcnt vmcnt(25)
	ds_write_b128 v6, v[148:151] offset:2048
	s_waitcnt vmcnt(24)
	ds_write_b128 v6, v[152:155] offset:3072
	s_waitcnt vmcnt(23)
	ds_write_b128 v6, v[156:159] offset:4096
	s_waitcnt vmcnt(22)
	ds_write_b128 v6, v[160:163] offset:5120
	s_waitcnt vmcnt(21)
	ds_write_b128 v6, v[164:167] offset:6144
	s_waitcnt vmcnt(20)
	ds_write_b128 v6, v[214:217] offset:7168
.Lma_staged:
	s_mov_b64 s[94:95], s[36:37]
	s_waitcnt lgkmcnt(0)
	s_barrier
	s_waitcnt vmcnt(8)
	ds_read_b128 v[32:35], v7
	ds_read_b128 v[36:39], v7 offset:1024
	ds_read_b128 v[40:43], v7 offset:2048
	ds_read_b128 v[44:47], v7 offset:3072
	ds_read_b128 v[48:51], v7 offset:4096
	ds_read_b128 v[52:55], v7 offset:5120
	ds_read_b128 v[56:59], v7 offset:6144
	ds_read_b128 v[60:63], v7 offset:7168
	ds_read_b128 v[240:243], v7 offset:8192
	ds_read_b128 v[244:247], v7 offset:9216
	ds_read_b128 v[248:251], v7 offset:10240
	ds_read_b128 v[252:255], v7 offset:11264
	s_waitcnt lgkmcnt(11)
	v_mfma_f32_16x16x32_f16 v[96:99], v[32:35], v[16:19], 0
	ds_read_b128 v[32:35], v7 offset:12288
	s_waitcnt lgkmcnt(11)
	v_mfma_f32_16x16x32_f16 v[96:99], v[36:39], v[20:23], v[96:99]
	ds_read_b128 v[36:39], v7 offset:13312
	s_waitcnt lgkmcnt(11)
	v_mfma_f32_16x16x32_f16 v[96:99], v[40:43], v[24:27], v[96:99]
	ds_read_b128 v[40:43], v7 offset:14336
	s_waitcnt lgkmcnt(11)
	v_mfma_f32_16x16x32_f16 v[96:99], v[44:47], v[28:31], v[96:99]
	ds_read_b128 v[44:47], v7 offset:15360
	s_waitcnt lgkmcnt(11)
	v_mfma_f32_16x16x32_f16 v[100:103], v[48:51], v[16:19], 0
	ds_read_b128 v[48:51], v7 offset:16384
	s_waitcnt lgkmcnt(11)
	v_mfma_f32_16x16x32_f16 v[100:103], v[52:55], v[20:23], v[100:103]
	ds_read_b128 v[52:55], v7 offset:17408
	s_waitcnt lgkmcnt(11)
	v_mfma_f32_16x16x32_f16 v[100:103], v[56:59], v[24:27], v[100:103]
	ds_read_b128 v[56:59], v7 offset:18432
	s_waitcnt lgkmcnt(11)
	v_mfma_f32_16x16x32_f16 v[100:103], v[60:63], v[28:31], v[100:103]
	ds_read_b128 v[60:63], v7 offset:19456
	s_waitcnt lgkmcnt(11)
	v_mfma_f32_16x16x32_f16 v[104:107], v[240:243], v[16:19], 0
	ds_read_b128 v[240:243], v7 offset:20480
	s_waitcnt lgkmcnt(11)
; __device__ __forceinline__ void mem_attn_phase(int wv, const Args& A, LAS unsigned char* lds, int G) {
;     ...
;         for (int kt = 0; kt < 16; ++kt) { f32x4 a = {0.f, 0.f, 0.f, 0.f};
; #pragma unroll
;             for (int ks = 0; ks < 4; ++ks) { const h16x8 kf = __builtin_bit_cast(h16x8, *(const u32x4*)(Kb + (size_t)(kt * 16 + fr) * 512 + h * 128 + ks * 32 + fq * 8)); a = __builtin_amdgcn_mfma_f32_16x16x32_f16(kf, qf[ks], a, 0, 0, 0); }
;             lg[kt] = a; m = fmaxf(m, fmaxf(fmaxf(a[0], a[1]), fmaxf(a[2], a[3]))); }
	v_mfma_f32_16x16x32_f16 v[104:107], v[244:247], v[20:23], v[104:107]
	ds_read_b128 v[244:247], v7 offset:21504
	s_waitcnt lgkmcnt(11)
	v_mfma_f32_16x16x32_f16 v[104:107], v[248:251], v[24:27], v[104:107]
	ds_read_b128 v[248:251], v7 offset:22528
	s_waitcnt lgkmcnt(11)
	v_mfma_f32_16x16x32_f16 v[104:107], v[252:255], v[28:31], v[104:107]
	ds_read_b128 v[252:255], v7 offset:23552
	s_waitcnt lgkmcnt(11)
	v_mfma_f32_16x16x32_f16 v[108:111], v[32:35], v[16:19], 0
	ds_read_b128 v[32:35], v7 offset:24576
	s_waitcnt lgkmcnt(11)
	v_mfma_f32_16x16x32_f16 v[108:111], v[36:39], v[20:23], v[108:111]
	ds_read_b128 v[36:39], v7 offset:25600
	s_waitcnt lgkmcnt(11)
	v_mfma_f32_16x16x32_f16 v[108:111], v[40:43], v[24:27], v[108:111]
	ds_read_b128 v[40:43], v7 offset:26624
	s_waitcnt lgkmcnt(11)
	v_mfma_f32_16x16x32_f16 v[108:111], v[44:47], v[28:31], v[108:111]
	ds_read_b128 v[44:47], v7 offset:27648
	s_waitcnt lgkmcnt(11)
	v_mfma_f32_16x16x32_f16 v[112:115], v[48:51], v[16:19], 0
	ds_read_b128 v[48:51], v7 offset:28672
	s_waitcnt lgkmcnt(11)
	v_mfma_f32_16x16x32_f16 v[112:115], v[52:55], v[20:23], v[112:115]
	ds_read_b128 v[52:55], v7 offset:29696
	s_waitcnt lgkmcnt(11)
	v_mfma_f32_16x16x32_f16 v[112:115], v[56:59], v[24:27], v[112:115]
	ds_read_b128 v[56:59], v7 offset:30720
	s_waitcnt lgkmcnt(11)
	v_mfma_f32_16x16x32_f16 v[112:115], v[60:63], v[28:31], v[112:115]
	ds_read_b128 v[60:63], v7 offset:31744
	s_waitcnt lgkmcnt(11)
	v_mfma_f32_16x16x32_f16 v[116:119], v[240:243], v[16:19], 0
	ds_read_b128 v[240:243], v7 offset:32768
	s_waitcnt lgkmcnt(11)
	v_mfma_f32_16x16x32_f16 v[116:119], v[244:247], v[20:23], v[116:119]
	ds_read_b128 v[244:247], v7 offset:33792
	s_waitcnt lgkmcnt(11)
	v_mfma_f32_16x16x32_f16 v[116:119], v[248:251], v[24:27], v[116:119]
	ds_read_b128 v[248:251], v7 offset:34816
	s_waitcnt lgkmcnt(11)
	v_mfma_f32_16x16x32_f16 v[116:119], v[252:255], v[28:31], v[116:119]
	ds_read_b128 v[252:255], v7 offset:35840
	s_waitcnt lgkmcnt(11)
	v_mfma_f32_16x16x32_f16 v[120:123], v[32:35], v[16:19], 0
	ds_read_b128 v[32:35], v7 offset:36864
	s_waitcnt lgkmcnt(11)
	v_mfma_f32_16x16x32_f16 v[120:123], v[36:39], v[20:23], v[120:123]
	ds_read_b128 v[36:39], v7 offset:37888
	s_waitcnt lgkmcnt(11)
	v_mfma_f32_16x16x32_f16 v[120:123], v[40:43], v[24:27], v[120:123]
	ds_read_b128 v[40:43], v7 offset:38912
	s_waitcnt lgkmcnt(11)
	v_mfma_f32_16x16x32_f16 v[120:123], v[44:47], v[28:31], v[120:123]
	ds_read_b128 v[44:47], v7 offset:39936
	s_waitcnt lgkmcnt(11)
	v_mfma_f32_16x16x32_f16 v[124:127], v[48:51], v[16:19], 0
	ds_read_b128 v[48:51], v7 offset:40960
	s_waitcnt lgkmcnt(11)
	v_mfma_f32_16x16x32_f16 v[124:127], v[52:55], v[20:23], v[124:127]
	ds_read_b128 v[52:55], v7 offset:41984
	s_waitcnt lgkmcnt(11)
	v_mfma_f32_16x16x32_f16 v[124:127], v[56:59], v[24:27], v[124:127]
	ds_read_b128 v[56:59], v7 offset:43008
	s_waitcnt lgkmcnt(11)
	v_mfma_f32_16x16x32_f16 v[124:127], v[60:63], v[28:31], v[124:127]
	ds_read_b128 v[60:63], v7 offset:44032
	s_waitcnt lgkmcnt(11)
	v_mfma_f32_16x16x32_f16 v[128:131], v[240:243], v[16:19], 0
	ds_read_b128 v[240:243], v7 offset:45056
	s_waitcnt lgkmcnt(11)
	v_mfma_f32_16x16x32_f16 v[128:131], v[244:247], v[20:23], v[128:131]
	ds_read_b128 v[244:247], v7 offset:46080
	s_waitcnt lgkmcnt(11)
	v_mfma_f32_16x16x32_f16 v[128:131], v[248:251], v[24:27], v[128:131]
	ds_read_b128 v[248:251], v7 offset:47104
	s_waitcnt lgkmcnt(11)
	v_mfma_f32_16x16x32_f16 v[128:131], v[252:255], v[28:31], v[128:131]
	ds_read_b128 v[252:255], v7 offset:48128
	s_waitcnt lgkmcnt(11)
	v_mfma_f32_16x16x32_f16 v[132:135], v[32:35], v[16:19], 0
	ds_read_b128 v[32:35], v7 offset:49152
	s_waitcnt lgkmcnt(11)
	v_mfma_f32_16x16x32_f16 v[132:135], v[36:39], v[20:23], v[132:135]
	ds_read_b128 v[36:39], v7 offset:50176
	s_waitcnt lgkmcnt(11)
	v_mfma_f32_16x16x32_f16 v[132:135], v[40:43], v[24:27], v[132:135]
	ds_read_b128 v[40:43], v7 offset:51200
	s_waitcnt lgkmcnt(11)
	v_mfma_f32_16x16x32_f16 v[132:135], v[44:47], v[28:31], v[132:135]
	ds_read_b128 v[44:47], v7 offset:52224
	s_waitcnt lgkmcnt(11)
	v_mfma_f32_16x16x32_f16 v[136:139], v[48:51], v[16:19], 0
	ds_read_b128 v[48:51], v7 offset:53248
	s_waitcnt lgkmcnt(11)
	v_mfma_f32_16x16x32_f16 v[136:139], v[52:55], v[20:23], v[136:139]
	ds_read_b128 v[52:55], v7 offset:54272
	s_waitcnt lgkmcnt(11)
	v_mfma_f32_16x16x32_f16 v[136:139], v[56:59], v[24:27], v[136:139]
	ds_read_b128 v[56:59], v7 offset:55296
	s_waitcnt lgkmcnt(11)
	v_mfma_f32_16x16x32_f16 v[136:139], v[60:63], v[28:31], v[136:139]
	ds_read_b128 v[60:63], v7 offset:56320
	s_waitcnt lgkmcnt(11)
	v_mfma_f32_16x16x32_f16 v[140:143], v[240:243], v[16:19], 0
	ds_read_b128 v[240:243], v7 offset:57344
	s_waitcnt lgkmcnt(11)
	v_mfma_f32_16x16x32_f16 v[140:143], v[244:247], v[20:23], v[140:143]
	ds_read_b128 v[244:247], v7 offset:58368
	s_waitcnt lgkmcnt(11)
	v_mfma_f32_16x16x32_f16 v[140:143], v[248:251], v[24:27], v[140:143]
	ds_read_b128 v[248:251], v7 offset:59392
	s_waitcnt lgkmcnt(11)
	v_mfma_f32_16x16x32_f16 v[140:143], v[252:255], v[28:31], v[140:143]
	ds_read_b128 v[252:255], v7 offset:60416
	s_waitcnt lgkmcnt(11)
	v_mfma_f32_16x16x32_f16 v[144:147], v[32:35], v[16:19], 0
	ds_read_b128 v[32:35], v7 offset:61440
	s_waitcnt lgkmcnt(11)
	v_mfma_f32_16x16x32_f16 v[144:147], v[36:39], v[20:23], v[144:147]
	ds_read_b128 v[36:39], v7 offset:62464
	s_waitcnt lgkmcnt(11)
	v_mfma_f32_16x16x32_f16 v[144:147], v[40:43], v[24:27], v[144:147]
	ds_read_b128 v[40:43], v7 offset:63488
	s_waitcnt lgkmcnt(11)
	v_mfma_f32_16x16x32_f16 v[144:147], v[44:47], v[28:31], v[144:147]
	ds_read_b128 v[44:47], v7 offset:64512
	s_waitcnt lgkmcnt(11)
; #define LAS __attribute__((address_space(3)))
; __device__ __forceinline__ void mem_attn_phase(int wv, const Args& A, LAS unsigned char* lds, int G) {
;     ...
;         for (int kt = 0; kt < 16; ++kt) { f32x4 a = {0.f, 0.f, 0.f, 0.f};
; #pragma unroll
;             for (int ks = 0; ks < 4; ++ks) { const h16x8 kf = __builtin_bit_cast(h16x8, *(const u32x4*)(Kb + (size_t)(kt * 16 + fr) * 512 + h * 128 + ks * 32 + fq * 8)); a = __builtin_amdgcn_mfma_f32_16x16x32_f16(kf, qf[ks], a, 0, 0, 0); }
;             lg[kt] = a; m = fmaxf(m, fmaxf(fmaxf(a[0], a[1]), fmaxf(a[2], a[3]))); }
;         m = fmaxf(m, __shfl_xor(m, 16)); m = fmaxf(m, __shfl_xor(m, 32));
;         float sm = 0.f;
; #pragma unroll
;         for (int kt = 0; kt < 16; ++kt) { h16x4 p4;
; #pragma unroll
;             for (int r = 0; r < 4; ++r) { const float p = __expf(lg[kt][r] - m); sm += p; p4[r] = (h16)p; }
;             *(LAS u32x2*)(Pw + fr * 264 + kt * 16 + fq * 4) = __builtin_bit_cast(u32x2, p4); }
;         sm += __shfl_xor(sm, 16); sm += __shfl_xor(sm, 32);
	v_mfma_f32_16x16x32_f16 v[148:151], v[48:51], v[16:19], 0
	s_waitcnt lgkmcnt(10)
	v_mfma_f32_16x16x32_f16 v[148:151], v[52:55], v[20:23], v[148:151]
	s_waitcnt lgkmcnt(9)
	v_mfma_f32_16x16x32_f16 v[148:151], v[56:59], v[24:27], v[148:151]
	s_waitcnt lgkmcnt(8)
	v_mfma_f32_16x16x32_f16 v[148:151], v[60:63], v[28:31], v[148:151]
	s_waitcnt lgkmcnt(7)
	v_mfma_f32_16x16x32_f16 v[152:155], v[240:243], v[16:19], 0
	s_waitcnt lgkmcnt(6)
	v_mfma_f32_16x16x32_f16 v[152:155], v[244:247], v[20:23], v[152:155]
	s_waitcnt lgkmcnt(5)
	v_mfma_f32_16x16x32_f16 v[152:155], v[248:251], v[24:27], v[152:155]
	s_waitcnt lgkmcnt(4)
	v_mfma_f32_16x16x32_f16 v[152:155], v[252:255], v[28:31], v[152:155]
	s_waitcnt lgkmcnt(3)
	v_mfma_f32_16x16x32_f16 v[156:159], v[32:35], v[16:19], 0
	s_waitcnt lgkmcnt(2)
	v_mfma_f32_16x16x32_f16 v[156:159], v[36:39], v[20:23], v[156:159]
	s_waitcnt lgkmcnt(1)
	v_mfma_f32_16x16x32_f16 v[156:159], v[40:43], v[24:27], v[156:159]
	s_waitcnt lgkmcnt(0)
	v_mfma_f32_16x16x32_f16 v[156:159], v[44:47], v[28:31], v[156:159]
	s_nop 7
	s_nop 1
	v_max3_f32 v13, v96, v97, v98
	v_max3_f32 v13, v13, v99, v100
	v_max3_f32 v13, v13, v101, v102
	v_max3_f32 v13, v13, v103, v104
	v_max3_f32 v13, v13, v105, v106
	v_max3_f32 v13, v13, v107, v108
	v_max3_f32 v13, v13, v109, v110
	v_max3_f32 v13, v13, v111, v112
	v_max3_f32 v13, v13, v113, v114
	v_max3_f32 v13, v13, v115, v116
	v_max3_f32 v13, v13, v117, v118
	v_max3_f32 v13, v13, v119, v120
	v_max3_f32 v13, v13, v121, v122
	v_max3_f32 v13, v13, v123, v124
	v_max3_f32 v13, v13, v125, v126
	v_max3_f32 v13, v13, v127, v128
	v_max3_f32 v13, v13, v129, v130
	v_max3_f32 v13, v13, v131, v132
	v_max3_f32 v13, v13, v133, v134
	v_max3_f32 v13, v13, v135, v136
	v_max3_f32 v13, v13, v137, v138
	v_max3_f32 v13, v13, v139, v140
	v_max3_f32 v13, v13, v141, v142
	v_max3_f32 v13, v13, v143, v144
	v_max3_f32 v13, v13, v145, v146
	v_max3_f32 v13, v13, v147, v148
	v_max3_f32 v13, v13, v149, v150
	v_max3_f32 v13, v13, v151, v152
	v_max3_f32 v13, v13, v153, v154
	v_max3_f32 v13, v13, v155, v156
	v_max3_f32 v13, v13, v157, v158
	v_max_f32_e32 v13, v13, v159
	ds_bpermute_b32 v64, v11, v13
	s_waitcnt lgkmcnt(0)
	v_max_f32_e32 v13, v13, v64
	ds_bpermute_b32 v64, v12, v13
	s_waitcnt lgkmcnt(0)
	v_max_f32_e32 v13, v13, v64
	v_mov_b32_e32 v14, 0
	v_sub_f32_e32 v96, v96, v13
	v_sub_f32_e32 v97, v97, v13
	v_sub_f32_e32 v98, v98, v13
	v_sub_f32_e32 v99, v99, v13
	v_mul_f32_e32 v96, 0x3fb8aa3b, v96
	v_mul_f32_e32 v97, 0x3fb8aa3b, v97
	v_mul_f32_e32 v98, 0x3fb8aa3b, v98
	v_mul_f32_e32 v99, 0x3fb8aa3b, v99
	v_exp_f32_e32 v96, v96
	v_exp_f32_e32 v97, v97
	v_exp_f32_e32 v98, v98
	v_exp_f32_e32 v99, v99
	s_nop 0
	v_add_f32_e32 v14, v14, v96
	v_add_f32_e32 v14, v14, v97
	v_add_f32_e32 v14, v14, v98
	v_add_f32_e32 v14, v14, v99
	v_cvt_pk_f16_f32 v64, v96, v97
	v_cvt_pk_f16_f32 v65, v98, v99
	ds_write_b64 v8, v[64:65]
	v_sub_f32_e32 v100, v100, v13
	v_sub_f32_e32 v101, v101, v13
	v_sub_f32_e32 v102, v102, v13
	v_sub_f32_e32 v103, v103, v13
	v_mul_f32_e32 v100, 0x3fb8aa3b, v100
	v_mul_f32_e32 v101, 0x3fb8aa3b, v101
	v_mul_f32_e32 v102, 0x3fb8aa3b, v102
	v_mul_f32_e32 v103, 0x3fb8aa3b, v103
	v_exp_f32_e32 v100, v100
	v_exp_f32_e32 v101, v101
	v_exp_f32_e32 v102, v102
	v_exp_f32_e32 v103, v103
	s_nop 0
	v_add_f32_e32 v14, v14, v100
	v_add_f32_e32 v14, v14, v101
	v_add_f32_e32 v14, v14, v102
	v_add_f32_e32 v14, v14, v103
	v_cvt_pk_f16_f32 v66, v100, v101
	v_cvt_pk_f16_f32 v67, v102, v103
	ds_write_b64 v8, v[66:67] offset:32
	v_sub_f32_e32 v104, v104, v13
	v_sub_f32_e32 v105, v105, v13
	v_sub_f32_e32 v106, v106, v13
	v_sub_f32_e32 v107, v107, v13
	v_mul_f32_e32 v104, 0x3fb8aa3b, v104
	v_mul_f32_e32 v105, 0x3fb8aa3b, v105
	v_mul_f32_e32 v106, 0x3fb8aa3b, v106
	v_mul_f32_e32 v107, 0x3fb8aa3b, v107
	v_exp_f32_e32 v104, v104
	v_exp_f32_e32 v105, v105
	v_exp_f32_e32 v106, v106
	v_exp_f32_e32 v107, v107
	s_nop 0
	v_add_f32_e32 v14, v14, v104
	v_add_f32_e32 v14, v14, v105
	v_add_f32_e32 v14, v14, v106
	v_add_f32_e32 v14, v14, v107
	v_cvt_pk_f16_f32 v64, v104, v105
	v_cvt_pk_f16_f32 v65, v106, v107
	ds_write_b64 v8, v[64:65] offset:64
	v_sub_f32_e32 v108, v108, v13
	v_sub_f32_e32 v109, v109, v13
	v_sub_f32_e32 v110, v110, v13
	v_sub_f32_e32 v111, v111, v13
	v_mul_f32_e32 v108, 0x3fb8aa3b, v108
	v_mul_f32_e32 v109, 0x3fb8aa3b, v109
	v_mul_f32_e32 v110, 0x3fb8aa3b, v110
	v_mul_f32_e32 v111, 0x3fb8aa3b, v111
	v_exp_f32_e32 v108, v108
	v_exp_f32_e32 v109, v109
	v_exp_f32_e32 v110, v110
	v_exp_f32_e32 v111, v111
	s_nop 0
	v_add_f32_e32 v14, v14, v108
	v_add_f32_e32 v14, v14, v109
	v_add_f32_e32 v14, v14, v110
	v_add_f32_e32 v14, v14, v111
	v_cvt_pk_f16_f32 v66, v108, v109
	v_cvt_pk_f16_f32 v67, v110, v111
	ds_write_b64 v8, v[66:67] offset:96
	v_sub_f32_e32 v112, v112, v13
	v_sub_f32_e32 v113, v113, v13
	v_sub_f32_e32 v114, v114, v13
	v_sub_f32_e32 v115, v115, v13
	v_mul_f32_e32 v112, 0x3fb8aa3b, v112
	v_mul_f32_e32 v113, 0x3fb8aa3b, v113
	v_mul_f32_e32 v114, 0x3fb8aa3b, v114
	v_mul_f32_e32 v115, 0x3fb8aa3b, v115
	v_exp_f32_e32 v112, v112
	v_exp_f32_e32 v113, v113
	v_exp_f32_e32 v114, v114
	v_exp_f32_e32 v115, v115
	s_nop 0
	v_add_f32_e32 v14, v14, v112
	v_add_f32_e32 v14, v14, v113
	v_add_f32_e32 v14, v14, v114
	v_add_f32_e32 v14, v14, v115
	v_cvt_pk_f16_f32 v64, v112, v113
	v_cvt_pk_f16_f32 v65, v114, v115
	ds_write_b64 v8, v[64:65] offset:128
	v_sub_f32_e32 v116, v116, v13
	v_sub_f32_e32 v117, v117, v13
	v_sub_f32_e32 v118, v118, v13
	v_sub_f32_e32 v119, v119, v13
	v_mul_f32_e32 v116, 0x3fb8aa3b, v116
	v_mul_f32_e32 v117, 0x3fb8aa3b, v117
	v_mul_f32_e32 v118, 0x3fb8aa3b, v118
	v_mul_f32_e32 v119, 0x3fb8aa3b, v119
	v_exp_f32_e32 v116, v116
	v_exp_f32_e32 v117, v117
; #define LAS __attribute__((address_space(3)))
; __device__ __forceinline__ void mem_attn_phase(int wv, const Args& A, LAS unsigned char* lds, int G) {
;     ...
;         for (int kt = 0; kt < 16; ++kt) { h16x4 p4;
; #pragma unroll
;             for (int r = 0; r < 4; ++r) { const float p = __expf(lg[kt][r] - m); sm += p; p4[r] = (h16)p; }
;             *(LAS u32x2*)(Pw + fr * 264 + kt * 16 + fq * 4) = __builtin_bit_cast(u32x2, p4); }
	v_exp_f32_e32 v118, v118
	v_exp_f32_e32 v119, v119
	s_nop 0
	v_add_f32_e32 v14, v14, v116
	v_add_f32_e32 v14, v14, v117
	v_add_f32_e32 v14, v14, v118
	v_add_f32_e32 v14, v14, v119
	v_cvt_pk_f16_f32 v66, v116, v117
	v_cvt_pk_f16_f32 v67, v118, v119
	ds_write_b64 v8, v[66:67] offset:160
	v_sub_f32_e32 v120, v120, v13
	v_sub_f32_e32 v121, v121, v13
	v_sub_f32_e32 v122, v122, v13
	v_sub_f32_e32 v123, v123, v13
	v_mul_f32_e32 v120, 0x3fb8aa3b, v120
	v_mul_f32_e32 v121, 0x3fb8aa3b, v121
	v_mul_f32_e32 v122, 0x3fb8aa3b, v122
	v_mul_f32_e32 v123, 0x3fb8aa3b, v123
	v_exp_f32_e32 v120, v120
	v_exp_f32_e32 v121, v121
	v_exp_f32_e32 v122, v122
	v_exp_f32_e32 v123, v123
	s_nop 0
	v_add_f32_e32 v14, v14, v120
	v_add_f32_e32 v14, v14, v121
	v_add_f32_e32 v14, v14, v122
	v_add_f32_e32 v14, v14, v123
	v_cvt_pk_f16_f32 v64, v120, v121
	v_cvt_pk_f16_f32 v65, v122, v123
	ds_write_b64 v8, v[64:65] offset:192
	v_sub_f32_e32 v124, v124, v13
	v_sub_f32_e32 v125, v125, v13
	v_sub_f32_e32 v126, v126, v13
	v_sub_f32_e32 v127, v127, v13
	v_mul_f32_e32 v124, 0x3fb8aa3b, v124
	v_mul_f32_e32 v125, 0x3fb8aa3b, v125
	v_mul_f32_e32 v126, 0x3fb8aa3b, v126
	v_mul_f32_e32 v127, 0x3fb8aa3b, v127
	v_exp_f32_e32 v124, v124
	v_exp_f32_e32 v125, v125
	v_exp_f32_e32 v126, v126
	v_exp_f32_e32 v127, v127
	s_nop 0
	v_add_f32_e32 v14, v14, v124
	v_add_f32_e32 v14, v14, v125
	v_add_f32_e32 v14, v14, v126
	v_add_f32_e32 v14, v14, v127
	v_cvt_pk_f16_f32 v66, v124, v125
	v_cvt_pk_f16_f32 v67, v126, v127
	ds_write_b64 v8, v[66:67] offset:224
	v_sub_f32_e32 v128, v128, v13
	v_sub_f32_e32 v129, v129, v13
	v_sub_f32_e32 v130, v130, v13
	v_sub_f32_e32 v131, v131, v13
	v_mul_f32_e32 v128, 0x3fb8aa3b, v128
	v_mul_f32_e32 v129, 0x3fb8aa3b, v129
	v_mul_f32_e32 v130, 0x3fb8aa3b, v130
	v_mul_f32_e32 v131, 0x3fb8aa3b, v131
	v_exp_f32_e32 v128, v128
	v_exp_f32_e32 v129, v129
	v_exp_f32_e32 v130, v130
	v_exp_f32_e32 v131, v131
	s_nop 0
	v_add_f32_e32 v14, v14, v128
	v_add_f32_e32 v14, v14, v129
	v_add_f32_e32 v14, v14, v130
	v_add_f32_e32 v14, v14, v131
	v_cvt_pk_f16_f32 v64, v128, v129
	v_cvt_pk_f16_f32 v65, v130, v131
	ds_write_b64 v8, v[64:65] offset:256
	v_sub_f32_e32 v132, v132, v13
	v_sub_f32_e32 v133, v133, v13
	v_sub_f32_e32 v134, v134, v13
	v_sub_f32_e32 v135, v135, v13
	v_mul_f32_e32 v132, 0x3fb8aa3b, v132
	v_mul_f32_e32 v133, 0x3fb8aa3b, v133
	v_mul_f32_e32 v134, 0x3fb8aa3b, v134
	v_mul_f32_e32 v135, 0x3fb8aa3b, v135
	v_exp_f32_e32 v132, v132
	v_exp_f32_e32 v133, v133
	v_exp_f32_e32 v134, v134
	v_exp_f32_e32 v135, v135
	s_nop 0
	v_add_f32_e32 v14, v14, v132
	v_add_f32_e32 v14, v14, v133
	v_add_f32_e32 v14, v14, v134
	v_add_f32_e32 v14, v14, v135
	v_cvt_pk_f16_f32 v66, v132, v133
	v_cvt_pk_f16_f32 v67, v134, v135
	ds_write_b64 v8, v[66:67] offset:288
	v_sub_f32_e32 v136, v136, v13
	v_sub_f32_e32 v137, v137, v13
	v_sub_f32_e32 v138, v138, v13
	v_sub_f32_e32 v139, v139, v13
	v_mul_f32_e32 v136, 0x3fb8aa3b, v136
	v_mul_f32_e32 v137, 0x3fb8aa3b, v137
	v_mul_f32_e32 v138, 0x3fb8aa3b, v138
	v_mul_f32_e32 v139, 0x3fb8aa3b, v139
	v_exp_f32_e32 v136, v136
	v_exp_f32_e32 v137, v137
	v_exp_f32_e32 v138, v138
	v_exp_f32_e32 v139, v139
	s_nop 0
	v_add_f32_e32 v14, v14, v136
	v_add_f32_e32 v14, v14, v137
	v_add_f32_e32 v14, v14, v138
	v_add_f32_e32 v14, v14, v139
	v_cvt_pk_f16_f32 v64, v136, v137
	v_cvt_pk_f16_f32 v65, v138, v139
	ds_write_b64 v8, v[64:65] offset:320
	v_sub_f32_e32 v140, v140, v13
	v_sub_f32_e32 v141, v141, v13
	v_sub_f32_e32 v142, v142, v13
	v_sub_f32_e32 v143, v143, v13
	v_mul_f32_e32 v140, 0x3fb8aa3b, v140
	v_mul_f32_e32 v141, 0x3fb8aa3b, v141
	v_mul_f32_e32 v142, 0x3fb8aa3b, v142
	v_mul_f32_e32 v143, 0x3fb8aa3b, v143
	v_exp_f32_e32 v140, v140
	v_exp_f32_e32 v141, v141
	v_exp_f32_e32 v142, v142
	v_exp_f32_e32 v143, v143
	s_nop 0
	v_add_f32_e32 v14, v14, v140
	v_add_f32_e32 v14, v14, v141
	v_add_f32_e32 v14, v14, v142
	v_add_f32_e32 v14, v14, v143
	v_cvt_pk_f16_f32 v66, v140, v141
	v_cvt_pk_f16_f32 v67, v142, v143
	ds_write_b64 v8, v[66:67] offset:352
	v_sub_f32_e32 v144, v144, v13
	v_sub_f32_e32 v145, v145, v13
	v_sub_f32_e32 v146, v146, v13
	v_sub_f32_e32 v147, v147, v13
	v_mul_f32_e32 v144, 0x3fb8aa3b, v144
	v_mul_f32_e32 v145, 0x3fb8aa3b, v145
	v_mul_f32_e32 v146, 0x3fb8aa3b, v146
	v_mul_f32_e32 v147, 0x3fb8aa3b, v147
	v_exp_f32_e32 v144, v144
	v_exp_f32_e32 v145, v145
	v_exp_f32_e32 v146, v146
	v_exp_f32_e32 v147, v147
	s_nop 0
	v_add_f32_e32 v14, v14, v144
	v_add_f32_e32 v14, v14, v145
	v_add_f32_e32 v14, v14, v146
	v_add_f32_e32 v14, v14, v147
	v_cvt_pk_f16_f32 v64, v144, v145
	v_cvt_pk_f16_f32 v65, v146, v147
	ds_write_b64 v8, v[64:65] offset:384
	v_sub_f32_e32 v148, v148, v13
	v_sub_f32_e32 v149, v149, v13
	v_sub_f32_e32 v150, v150, v13
	v_sub_f32_e32 v151, v151, v13
	v_mul_f32_e32 v148, 0x3fb8aa3b, v148
	v_mul_f32_e32 v149, 0x3fb8aa3b, v149
	v_mul_f32_e32 v150, 0x3fb8aa3b, v150
	v_mul_f32_e32 v151, 0x3fb8aa3b, v151
	v_exp_f32_e32 v148, v148
	v_exp_f32_e32 v149, v149
	v_exp_f32_e32 v150, v150
	v_exp_f32_e32 v151, v151
	s_nop 0
	v_add_f32_e32 v14, v14, v148
	v_add_f32_e32 v14, v14, v149
	v_add_f32_e32 v14, v14, v150
	v_add_f32_e32 v14, v14, v151
	v_cvt_pk_f16_f32 v66, v148, v149
	v_cvt_pk_f16_f32 v67, v150, v151
	ds_write_b64 v8, v[66:67] offset:416
	v_sub_f32_e32 v152, v152, v13
	v_sub_f32_e32 v153, v153, v13
	v_sub_f32_e32 v154, v154, v13
	v_sub_f32_e32 v155, v155, v13
	v_mul_f32_e32 v152, 0x3fb8aa3b, v152
	v_mul_f32_e32 v153, 0x3fb8aa3b, v153
	v_mul_f32_e32 v154, 0x3fb8aa3b, v154
	v_mul_f32_e32 v155, 0x3fb8aa3b, v155
	v_exp_f32_e32 v152, v152
	v_exp_f32_e32 v153, v153
	v_exp_f32_e32 v154, v154
	v_exp_f32_e32 v155, v155
	s_nop 0
	v_add_f32_e32 v14, v14, v152
	v_add_f32_e32 v14, v14, v153
	v_add_f32_e32 v14, v14, v154
	v_add_f32_e32 v14, v14, v155
	v_cvt_pk_f16_f32 v64, v152, v153
	v_cvt_pk_f16_f32 v65, v154, v155
	ds_write_b64 v8, v[64:65] offset:448
	v_sub_f32_e32 v156, v156, v13
	v_sub_f32_e32 v157, v157, v13
	v_sub_f32_e32 v158, v158, v13
	v_sub_f32_e32 v159, v159, v13
	v_mul_f32_e32 v156, 0x3fb8aa3b, v156
	v_mul_f32_e32 v157, 0x3fb8aa3b, v157
	v_mul_f32_e32 v158, 0x3fb8aa3b, v158
	v_mul_f32_e32 v159, 0x3fb8aa3b, v159
	v_exp_f32_e32 v156, v156
	v_exp_f32_e32 v157, v157
	v_exp_f32_e32 v158, v158
	v_exp_f32_e32 v159, v159
	s_nop 0
	v_add_f32_e32 v14, v14, v156
	v_add_f32_e32 v14, v14, v157
	v_add_f32_e32 v14, v14, v158
	v_add_f32_e32 v14, v14, v159
	v_cvt_pk_f16_f32 v66, v156, v157
	v_cvt_pk_f16_f32 v67, v158, v159
	ds_write_b64 v8, v[66:67] offset:480
	ds_bpermute_b32 v68, v11, v14
	s_waitcnt lgkmcnt(0)
; #define LAS __attribute__((address_space(3)))
; __device__ __forceinline__ void mem_attn_phase(int wv, const Args& A, LAS unsigned char* lds, int G) {
;     ...
;     for (int wu = blockIdx.x * 8 + w; wu < (MT / 16) * 4; wu += G * 8) {
;         const int blk = wu >> 3; const int h = blk & 3, tile = (blk >> 2) * 8 + (wu & 7); const size_t row0 = (size_t)tile * 16;
;         const h16* Kb; const h16* VTb;
;         if (row0 < NP) { const int b = (int)(row0 >> 14); Kb = (const h16*)(ws + WS_MK16) + (size_t)b * 256 * 512; VTb = (const h16*)(ws + WS_MVT) + (size_t)(b * 4 + h) * 32768; }
;         else { const int bs = (int)((row0 - NP) >> 6); Kb = (const h16*)(ws + WS_CMK) + (size_t)bs * 256 * 512; VTb = (const h16*)(ws + WS_CMVT) + (size_t)(bs * 4 + h) * 32768; }
;         h16x8 qf[4];
; #pragma unroll
;         for (int ks = 0; ks < 4; ++ks) qf[ks] = __builtin_bit_cast(h16x8, *(const u32x4*)(MQ + (row0 + fr) * 512 + h * 128 + ks * 32 + fq * 8));
;     ...
;         sm += __shfl_xor(sm, 16); sm += __shfl_xor(sm, 32);
;         const float inv = 1.f / sm;
; #pragma unroll
;         for (int db = 0; db < 8; ++db) { f32x4 o = {0.f, 0.f, 0.f, 0.f};
; #pragma unroll
;             for (int ks = 0; ks < 8; ++ks) { const h16x8 vf = __builtin_bit_cast(h16x8, *(const u32x4*)(VTb + (size_t)(db * 16 + fr) * 256 + ks * 32 + fq * 8));
;                 const h16x8 pf = *(const LAS h16x8*)(Pw + fr * 264 + ks * 32 + fq * 8); o = __builtin_amdgcn_mfma_f32_16x16x32_f16(vf, pf, o, 0, 0, 0); }
;             h16x4 o4; o4[0] = (h16)(o[0] * inv); o4[1] = (h16)(o[1] * inv); o4[2] = (h16)(o[2] * inv); o4[3] = (h16)(o[3] * inv);
;             *(u32x2*)(MO + (row0 + fr) * 512 + h * 128 + db * 16 + fq * 4) = __builtin_bit_cast(u32x2, o4); }
	v_add_f32_e32 v14, v14, v68
	ds_bpermute_b32 v68, v12, v14
	s_waitcnt lgkmcnt(0)
	v_add_f32_e32 v14, v14, v68
	v_div_scale_f32 v64, s[34:35], v14, v14, 1.0
	v_div_scale_f32 v67, vcc, 1.0, v14, 1.0
	v_rcp_f32_e32 v65, v64
	s_nop 0
	v_fma_f32 v66, -v64, v65, 1.0
	v_fmac_f32_e32 v65, v66, v65
	v_mul_f32_e32 v68, v67, v65
	v_fma_f32 v69, -v64, v68, v67
	v_fmac_f32_e32 v68, v69, v65
	v_fma_f32 v64, -v64, v68, v67
	v_div_fmas_f32 v70, v64, v65, v68
	v_div_fixup_f32 v15, v70, v14, 1.0
	ds_read_b128 v[96:99], v9
	ds_read_b128 v[100:103], v9 offset:64
	ds_read_b128 v[104:107], v9 offset:128
	ds_read_b128 v[108:111], v9 offset:192
	ds_read_b128 v[112:115], v9 offset:256
	ds_read_b128 v[116:119], v9 offset:320
	ds_read_b128 v[120:123], v9 offset:384
	ds_read_b128 v[124:127], v9 offset:448
	s_barrier
	s_waitcnt vmcnt(0)
	ds_write_b128 v6, v[182:185]
	ds_write_b128 v6, v[186:189] offset:1024
	ds_write_b128 v6, v[190:193] offset:2048
	ds_write_b128 v6, v[194:197] offset:3072
	ds_write_b128 v6, v[198:201] offset:4096
	ds_write_b128 v6, v[202:205] offset:5120
	ds_write_b128 v6, v[206:209] offset:6144
	ds_write_b128 v6, v[210:213] offset:7168
	s_waitcnt lgkmcnt(0)
	s_barrier
	s_add_i32 s77, s71, 1
	s_cmp_lt_u32 s77, 4
	s_cbranch_scc0 .Lma_nopf
	s_lshl_b32 s72, s77, 8
	s_add_i32 s73, s2, s72
	s_and_b32 s74, s73, 3
	s_lshr_b32 s75, s73, 2
	s_lshl_b32 s75, s75, 3
	s_add_i32 s75, s75, s70
	s_lshr_b32 s76, s75, 10
	s_lshl_b32 s32, s76, 18
	s_lshl_b32 s33, s74, 8
	s_add_i32 s32, s32, s33
	s_lshl_b32 s33, s70, 15
	s_add_i32 s32, s32, s33
	s_add_u32 s78, s44, 0x3cc4d000
	s_addc_u32 s79, s45, 0
	s_add_u32 s78, s78, s32
	s_addc_u32 s79, s79, 0
	s_add_u32 s88, s78, 0x4000
	s_addc_u32 s89, s79, 0
	s_lshl_b32 s32, s76, 2
	s_add_i32 s32, s32, s74
	s_lshl_b32 s32, s32, 16
	s_lshl_b32 s33, s70, 13
	s_add_i32 s32, s32, s33
	s_add_u32 s90, s44, 0x3cccd000
	s_addc_u32 s91, s45, 0
	s_add_u32 s90, s90, s32
	s_addc_u32 s91, s91, 0
	s_lshl_b32 s32, s75, 14
	s_lshl_b32 s33, s74, 8
	s_add_i32 s32, s32, s33
	s_add_u32 s92, s44, 0x324c1000
	s_addc_u32 s93, s45, 0
	s_add_u32 s92, s92, s32
	s_addc_u32 s93, s93, 0
	s_add_u32 s36, s44, 0x34541000
	s_addc_u32 s37, s45, 0
	s_add_u32 s36, s36, s32
	s_addc_u32 s37, s37, 0
	global_load_dwordx4 v[140:143], v4, s[78:79]
	global_load_dwordx4 v[144:147], v4, s[78:79] offset:64
	global_load_dwordx4 v[148:151], v4, s[78:79] offset:128
	global_load_dwordx4 v[152:155], v4, s[78:79] offset:192
	global_load_dwordx4 v[156:159], v4, s[88:89]
	global_load_dwordx4 v[160:163], v4, s[88:89] offset:64
	global_load_dwordx4 v[164:167], v4, s[88:89] offset:128
	global_load_dwordx4 v[214:217], v4, s[88:89] offset:192
	global_load_dwordx4 v[16:19], v4, s[92:93]
	global_load_dwordx4 v[20:23], v4, s[92:93] offset:64
	global_load_dwordx4 v[24:27], v4, s[92:93] offset:128
	global_load_dwordx4 v[28:31], v4, s[92:93] offset:192
	global_load_dwordx4 v[182:185], v5, s[90:91]
	global_load_dwordx4 v[186:189], v5, s[90:91] offset:64
	global_load_dwordx4 v[190:193], v5, s[90:91] offset:128
	global_load_dwordx4 v[194:197], v5, s[90:91] offset:192
	global_load_dwordx4 v[198:201], v5, s[90:91] offset:256
	global_load_dwordx4 v[202:205], v5, s[90:91] offset:320
	global_load_dwordx4 v[206:209], v5, s[90:91] offset:384
	global_load_dwordx4 v[210:213], v5, s[90:91] offset:448
.Lma_nopf:
	ds_read_b128 v[32:35], v7
	ds_read_b128 v[36:39], v7 offset:1024
	ds_read_b128 v[40:43], v7 offset:2048
	ds_read_b128 v[44:47], v7 offset:3072
	ds_read_b128 v[48:51], v7 offset:4096
	ds_read_b128 v[52:55], v7 offset:5120
	ds_read_b128 v[56:59], v7 offset:6144
	ds_read_b128 v[60:63], v7 offset:7168
	ds_read_b128 v[240:243], v7 offset:8192
	ds_read_b128 v[244:247], v7 offset:9216
	ds_read_b128 v[248:251], v7 offset:10240
	ds_read_b128 v[252:255], v7 offset:11264
	s_waitcnt lgkmcnt(11)
	v_mfma_f32_16x16x32_f16 v[128:131], v[32:35], v[96:99], 0
	ds_read_b128 v[32:35], v7 offset:12288
	s_waitcnt lgkmcnt(11)
	v_mfma_f32_16x16x32_f16 v[128:131], v[36:39], v[100:103], v[128:131]
	ds_read_b128 v[36:39], v7 offset:13312
	s_waitcnt lgkmcnt(11)
	v_mfma_f32_16x16x32_f16 v[128:131], v[40:43], v[104:107], v[128:131]
	ds_read_b128 v[40:43], v7 offset:14336
	s_waitcnt lgkmcnt(11)
	v_mfma_f32_16x16x32_f16 v[128:131], v[44:47], v[108:111], v[128:131]
	ds_read_b128 v[44:47], v7 offset:15360
	s_waitcnt lgkmcnt(11)
	v_mfma_f32_16x16x32_f16 v[128:131], v[48:51], v[112:115], v[128:131]
	ds_read_b128 v[48:51], v7 offset:16384
	s_waitcnt lgkmcnt(11)
	v_mfma_f32_16x16x32_f16 v[128:131], v[52:55], v[116:119], v[128:131]
	ds_read_b128 v[52:55], v7 offset:17408
	s_waitcnt lgkmcnt(11)
	v_mfma_f32_16x16x32_f16 v[128:131], v[56:59], v[120:123], v[128:131]
	ds_read_b128 v[56:59], v7 offset:18432
	s_waitcnt lgkmcnt(11)
	v_mfma_f32_16x16x32_f16 v[128:131], v[60:63], v[124:127], v[128:131]
	ds_read_b128 v[60:63], v7 offset:19456
	s_waitcnt lgkmcnt(11)
	v_mfma_f32_16x16x32_f16 v[132:135], v[240:243], v[96:99], 0
	ds_read_b128 v[240:243], v7 offset:20480
	s_waitcnt lgkmcnt(11)
	v_mfma_f32_16x16x32_f16 v[132:135], v[244:247], v[100:103], v[132:135]
	ds_read_b128 v[244:247], v7 offset:21504
	s_waitcnt lgkmcnt(11)
	v_mfma_f32_16x16x32_f16 v[132:135], v[248:251], v[104:107], v[132:135]
	ds_read_b128 v[248:251], v7 offset:22528
	s_waitcnt lgkmcnt(11)
	v_mfma_f32_16x16x32_f16 v[132:135], v[252:255], v[108:111], v[132:135]
	ds_read_b128 v[252:255], v7 offset:23552
	s_waitcnt lgkmcnt(11)
	v_mul_f32_e32 v128, v128, v15
	v_mul_f32_e32 v129, v129, v15
	v_mul_f32_e32 v130, v130, v15
	v_mul_f32_e32 v131, v131, v15
	v_cvt_pk_f16_f32 v136, v128, v129
	v_cvt_pk_f16_f32 v137, v130, v131
	global_store_dwordx2 v10, v[136:137], s[94:95]
	v_mfma_f32_16x16x32_f16 v[132:135], v[32:35], v[112:115], v[132:135]
	ds_read_b128 v[32:35], v7 offset:24576
	s_waitcnt lgkmcnt(11)
; #define LAS __attribute__((address_space(3)))
; __device__ __forceinline__ void mem_attn_phase(int wv, const Args& A, LAS unsigned char* lds, int G) {
;     ...
;         for (int db = 0; db < 8; ++db) { f32x4 o = {0.f, 0.f, 0.f, 0.f};
; #pragma unroll
;             for (int ks = 0; ks < 8; ++ks) { const h16x8 vf = __builtin_bit_cast(h16x8, *(const u32x4*)(VTb + (size_t)(db * 16 + fr) * 256 + ks * 32 + fq * 8));
;                 const h16x8 pf = *(const LAS h16x8*)(Pw + fr * 264 + ks * 32 + fq * 8); o = __builtin_amdgcn_mfma_f32_16x16x32_f16(vf, pf, o, 0, 0, 0); }
;             h16x4 o4; o4[0] = (h16)(o[0] * inv); o4[1] = (h16)(o[1] * inv); o4[2] = (h16)(o[2] * inv); o4[3] = (h16)(o[3] * inv);
;             *(u32x2*)(MO + (row0 + fr) * 512 + h * 128 + db * 16 + fq * 4) = __builtin_bit_cast(u32x2, o4); }
	v_mfma_f32_16x16x32_f16 v[132:135], v[36:39], v[116:119], v[132:135]
	ds_read_b128 v[36:39], v7 offset:25600
	s_waitcnt lgkmcnt(11)
	v_mfma_f32_16x16x32_f16 v[132:135], v[40:43], v[120:123], v[132:135]
	ds_read_b128 v[40:43], v7 offset:26624
	s_waitcnt lgkmcnt(11)
	v_mfma_f32_16x16x32_f16 v[132:135], v[44:47], v[124:127], v[132:135]
	ds_read_b128 v[44:47], v7 offset:27648
	s_waitcnt lgkmcnt(11)
	v_mfma_f32_16x16x32_f16 v[128:131], v[48:51], v[96:99], 0
	ds_read_b128 v[48:51], v7 offset:28672
	s_waitcnt lgkmcnt(11)
	v_mfma_f32_16x16x32_f16 v[128:131], v[52:55], v[100:103], v[128:131]
	ds_read_b128 v[52:55], v7 offset:29696
	s_waitcnt lgkmcnt(11)
	v_mfma_f32_16x16x32_f16 v[128:131], v[56:59], v[104:107], v[128:131]
	ds_read_b128 v[56:59], v7 offset:30720
	s_waitcnt lgkmcnt(11)
	v_mfma_f32_16x16x32_f16 v[128:131], v[60:63], v[108:111], v[128:131]
	ds_read_b128 v[60:63], v7 offset:31744
	s_waitcnt lgkmcnt(11)
	v_mul_f32_e32 v132, v132, v15
	v_mul_f32_e32 v133, v133, v15
	v_mul_f32_e32 v134, v134, v15
	v_mul_f32_e32 v135, v135, v15
	v_cvt_pk_f16_f32 v138, v132, v133
	v_cvt_pk_f16_f32 v139, v134, v135
	global_store_dwordx2 v10, v[138:139], s[94:95] offset:32
	v_mfma_f32_16x16x32_f16 v[128:131], v[240:243], v[112:115], v[128:131]
	ds_read_b128 v[240:243], v7 offset:32768
	s_waitcnt lgkmcnt(11)
	v_mfma_f32_16x16x32_f16 v[128:131], v[244:247], v[116:119], v[128:131]
	ds_read_b128 v[244:247], v7 offset:33792
	s_waitcnt lgkmcnt(11)
	v_mfma_f32_16x16x32_f16 v[128:131], v[248:251], v[120:123], v[128:131]
	ds_read_b128 v[248:251], v7 offset:34816
	s_waitcnt lgkmcnt(11)
	v_mfma_f32_16x16x32_f16 v[128:131], v[252:255], v[124:127], v[128:131]
	ds_read_b128 v[252:255], v7 offset:35840
	s_waitcnt lgkmcnt(11)
	v_mfma_f32_16x16x32_f16 v[132:135], v[32:35], v[96:99], 0
	ds_read_b128 v[32:35], v7 offset:36864
	s_waitcnt lgkmcnt(11)
	v_mfma_f32_16x16x32_f16 v[132:135], v[36:39], v[100:103], v[132:135]
	ds_read_b128 v[36:39], v7 offset:37888
	s_waitcnt lgkmcnt(11)
	v_mfma_f32_16x16x32_f16 v[132:135], v[40:43], v[104:107], v[132:135]
	ds_read_b128 v[40:43], v7 offset:38912
	s_waitcnt lgkmcnt(11)
	v_mfma_f32_16x16x32_f16 v[132:135], v[44:47], v[108:111], v[132:135]
	ds_read_b128 v[44:47], v7 offset:39936
	s_waitcnt lgkmcnt(11)
	v_mul_f32_e32 v128, v128, v15
	v_mul_f32_e32 v129, v129, v15
	v_mul_f32_e32 v130, v130, v15
	v_mul_f32_e32 v131, v131, v15
	v_cvt_pk_f16_f32 v136, v128, v129
	v_cvt_pk_f16_f32 v137, v130, v131
	global_store_dwordx2 v10, v[136:137], s[94:95] offset:64
	v_mfma_f32_16x16x32_f16 v[132:135], v[48:51], v[112:115], v[132:135]
	ds_read_b128 v[48:51], v7 offset:40960
	s_waitcnt lgkmcnt(11)
	v_mfma_f32_16x16x32_f16 v[132:135], v[52:55], v[116:119], v[132:135]
	ds_read_b128 v[52:55], v7 offset:41984
	s_waitcnt lgkmcnt(11)
	v_mfma_f32_16x16x32_f16 v[132:135], v[56:59], v[120:123], v[132:135]
	ds_read_b128 v[56:59], v7 offset:43008
	s_waitcnt lgkmcnt(11)
	v_mfma_f32_16x16x32_f16 v[132:135], v[60:63], v[124:127], v[132:135]
	ds_read_b128 v[60:63], v7 offset:44032
	s_waitcnt lgkmcnt(11)
	v_mfma_f32_16x16x32_f16 v[128:131], v[240:243], v[96:99], 0
	ds_read_b128 v[240:243], v7 offset:45056
	s_waitcnt lgkmcnt(11)
	v_mfma_f32_16x16x32_f16 v[128:131], v[244:247], v[100:103], v[128:131]
	ds_read_b128 v[244:247], v7 offset:46080
	s_waitcnt lgkmcnt(11)
	v_mfma_f32_16x16x32_f16 v[128:131], v[248:251], v[104:107], v[128:131]
	ds_read_b128 v[248:251], v7 offset:47104
	s_waitcnt lgkmcnt(11)
	v_mfma_f32_16x16x32_f16 v[128:131], v[252:255], v[108:111], v[128:131]
	ds_read_b128 v[252:255], v7 offset:48128
	s_waitcnt lgkmcnt(11)
	v_mul_f32_e32 v132, v132, v15
	v_mul_f32_e32 v133, v133, v15
	v_mul_f32_e32 v134, v134, v15
	v_mul_f32_e32 v135, v135, v15
	v_cvt_pk_f16_f32 v138, v132, v133
	v_cvt_pk_f16_f32 v139, v134, v135
	global_store_dwordx2 v10, v[138:139], s[94:95] offset:96
	v_mfma_f32_16x16x32_f16 v[128:131], v[32:35], v[112:115], v[128:131]
	ds_read_b128 v[32:35], v7 offset:49152
	s_waitcnt lgkmcnt(11)
	v_mfma_f32_16x16x32_f16 v[128:131], v[36:39], v[116:119], v[128:131]
	ds_read_b128 v[36:39], v7 offset:50176
	s_waitcnt lgkmcnt(11)
	v_mfma_f32_16x16x32_f16 v[128:131], v[40:43], v[120:123], v[128:131]
	ds_read_b128 v[40:43], v7 offset:51200
	s_waitcnt lgkmcnt(11)
	v_mfma_f32_16x16x32_f16 v[128:131], v[44:47], v[124:127], v[128:131]
	ds_read_b128 v[44:47], v7 offset:52224
	s_waitcnt lgkmcnt(11)
	v_mfma_f32_16x16x32_f16 v[132:135], v[48:51], v[96:99], 0
	ds_read_b128 v[48:51], v7 offset:53248
	s_waitcnt lgkmcnt(11)
	v_mfma_f32_16x16x32_f16 v[132:135], v[52:55], v[100:103], v[132:135]
	ds_read_b128 v[52:55], v7 offset:54272
	s_waitcnt lgkmcnt(11)
	v_mfma_f32_16x16x32_f16 v[132:135], v[56:59], v[104:107], v[132:135]
	ds_read_b128 v[56:59], v7 offset:55296
	s_waitcnt lgkmcnt(11)
	v_mfma_f32_16x16x32_f16 v[132:135], v[60:63], v[108:111], v[132:135]
	ds_read_b128 v[60:63], v7 offset:56320
	s_waitcnt lgkmcnt(11)
; #define LAS __attribute__((address_space(3)))
; __device__ __forceinline__ int opaque_tid(int wv) { int t = wv * 64 + (int)__builtin_amdgcn_mbcnt_hi(~0u, __builtin_amdgcn_mbcnt_lo(~0u, 0u)); asm volatile("" : "+v"(t)); return t; }
; __device__ __forceinline__ void mem_attn_phase(int wv, const Args& A, LAS unsigned char* lds, int G) {
;     const int tid = opaque_tid(wv), lane = tid & 63, w = tid >> 6, fr = lane & 15, fq = lane >> 4;
;     unsigned char* ws = A.ws;
;     const h16* MQ = (const h16*)(ws + WS_MQ); h16* MO = (h16*)(ws + WS_MO);
;     LAS h16* Pw = (LAS h16*)(lds + w * 8448);
;     for (int wu = blockIdx.x * 8 + w; wu < (MT / 16) * 4; wu += G * 8) {
;         const int blk = wu >> 3; const int h = blk & 3, tile = (blk >> 2) * 8 + (wu & 7); const size_t row0 = (size_t)tile * 16;
;         const h16* Kb; const h16* VTb;
;         if (row0 < NP) { const int b = (int)(row0 >> 14); Kb = (const h16*)(ws + WS_MK16) + (size_t)b * 256 * 512; VTb = (const h16*)(ws + WS_MVT) + (size_t)(b * 4 + h) * 32768; }
;         else { const int bs = (int)((row0 - NP) >> 6); Kb = (const h16*)(ws + WS_CMK) + (size_t)bs * 256 * 512; VTb = (const h16*)(ws + WS_CMVT) + (size_t)(bs * 4 + h) * 32768; }
;     ...
;         for (int db = 0; db < 8; ++db) { f32x4 o = {0.f, 0.f, 0.f, 0.f};
; #pragma unroll
;             for (int ks = 0; ks < 8; ++ks) { const h16x8 vf = __builtin_bit_cast(h16x8, *(const u32x4*)(VTb + (size_t)(db * 16 + fr) * 256 + ks * 32 + fq * 8));
;                 const h16x8 pf = *(const LAS h16x8*)(Pw + fr * 264 + ks * 32 + fq * 8); o = __builtin_amdgcn_mfma_f32_16x16x32_f16(vf, pf, o, 0, 0, 0); }
;             h16x4 o4; o4[0] = (h16)(o[0] * inv); o4[1] = (h16)(o[1] * inv); o4[2] = (h16)(o[2] * inv); o4[3] = (h16)(o[3] * inv);
;             *(u32x2*)(MO + (row0 + fr) * 512 + h * 128 + db * 16 + fq * 4) = __builtin_bit_cast(u32x2, o4); }
	v_mul_f32_e32 v128, v128, v15
	v_mul_f32_e32 v129, v129, v15
	v_mul_f32_e32 v130, v130, v15
	v_mul_f32_e32 v131, v131, v15
	v_cvt_pk_f16_f32 v136, v128, v129
	v_cvt_pk_f16_f32 v137, v130, v131
	global_store_dwordx2 v10, v[136:137], s[94:95] offset:128
	v_mfma_f32_16x16x32_f16 v[132:135], v[240:243], v[112:115], v[132:135]
	ds_read_b128 v[240:243], v7 offset:57344
	s_waitcnt lgkmcnt(11)
	v_mfma_f32_16x16x32_f16 v[132:135], v[244:247], v[116:119], v[132:135]
	ds_read_b128 v[244:247], v7 offset:58368
	s_waitcnt lgkmcnt(11)
	v_mfma_f32_16x16x32_f16 v[132:135], v[248:251], v[120:123], v[132:135]
	ds_read_b128 v[248:251], v7 offset:59392
	s_waitcnt lgkmcnt(11)
	v_mfma_f32_16x16x32_f16 v[132:135], v[252:255], v[124:127], v[132:135]
	ds_read_b128 v[252:255], v7 offset:60416
	s_waitcnt lgkmcnt(11)
	v_mfma_f32_16x16x32_f16 v[128:131], v[32:35], v[96:99], 0
	ds_read_b128 v[32:35], v7 offset:61440
	s_waitcnt lgkmcnt(11)
	v_mfma_f32_16x16x32_f16 v[128:131], v[36:39], v[100:103], v[128:131]
	ds_read_b128 v[36:39], v7 offset:62464
	s_waitcnt lgkmcnt(11)
	v_mfma_f32_16x16x32_f16 v[128:131], v[40:43], v[104:107], v[128:131]
	ds_read_b128 v[40:43], v7 offset:63488
	s_waitcnt lgkmcnt(11)
	v_mfma_f32_16x16x32_f16 v[128:131], v[44:47], v[108:111], v[128:131]
	ds_read_b128 v[44:47], v7 offset:64512
	s_waitcnt lgkmcnt(11)
	v_mul_f32_e32 v132, v132, v15
	v_mul_f32_e32 v133, v133, v15
	v_mul_f32_e32 v134, v134, v15
	v_mul_f32_e32 v135, v135, v15
	v_cvt_pk_f16_f32 v138, v132, v133
	v_cvt_pk_f16_f32 v139, v134, v135
	global_store_dwordx2 v10, v[138:139], s[94:95] offset:160
	v_mfma_f32_16x16x32_f16 v[128:131], v[48:51], v[112:115], v[128:131]
	s_waitcnt lgkmcnt(10)
	v_mfma_f32_16x16x32_f16 v[128:131], v[52:55], v[116:119], v[128:131]
	s_waitcnt lgkmcnt(9)
	v_mfma_f32_16x16x32_f16 v[128:131], v[56:59], v[120:123], v[128:131]
	s_waitcnt lgkmcnt(8)
	v_mfma_f32_16x16x32_f16 v[128:131], v[60:63], v[124:127], v[128:131]
	s_waitcnt lgkmcnt(7)
	v_mfma_f32_16x16x32_f16 v[132:135], v[240:243], v[96:99], 0
	s_waitcnt lgkmcnt(6)
	v_mfma_f32_16x16x32_f16 v[132:135], v[244:247], v[100:103], v[132:135]
	s_waitcnt lgkmcnt(5)
	v_mfma_f32_16x16x32_f16 v[132:135], v[248:251], v[104:107], v[132:135]
	s_waitcnt lgkmcnt(4)
	v_mfma_f32_16x16x32_f16 v[132:135], v[252:255], v[108:111], v[132:135]
	s_waitcnt lgkmcnt(3)
	v_mul_f32_e32 v128, v128, v15
	v_mul_f32_e32 v129, v129, v15
	v_mul_f32_e32 v130, v130, v15
	v_mul_f32_e32 v131, v131, v15
	v_cvt_pk_f16_f32 v136, v128, v129
	v_cvt_pk_f16_f32 v137, v130, v131
	global_store_dwordx2 v10, v[136:137], s[94:95] offset:192
	v_mfma_f32_16x16x32_f16 v[132:135], v[32:35], v[112:115], v[132:135]
	s_waitcnt lgkmcnt(2)
	v_mfma_f32_16x16x32_f16 v[132:135], v[36:39], v[116:119], v[132:135]
	s_waitcnt lgkmcnt(1)
	v_mfma_f32_16x16x32_f16 v[132:135], v[40:43], v[120:123], v[132:135]
	s_waitcnt lgkmcnt(0)
	v_mfma_f32_16x16x32_f16 v[132:135], v[44:47], v[124:127], v[132:135]
	s_nop 7
	s_nop 1
	v_mul_f32_e32 v132, v132, v15
	v_mul_f32_e32 v133, v133, v15
	v_mul_f32_e32 v134, v134, v15
	v_mul_f32_e32 v135, v135, v15
	v_cvt_pk_f16_f32 v138, v132, v133
	v_cvt_pk_f16_f32 v139, v134, v135
	global_store_dwordx2 v10, v[138:139], s[94:95] offset:224
	s_add_i32 s71, s71, 1
	s_cmp_lt_u32 s71, 4
	s_cbranch_scc1 .Lma_round
	s_waitcnt vmcnt(0)
	v_mov_b32_e32 v0, v170
	s_movk_i32 s0, 0x2080
	v_ashrrev_i32_e32 v1, 6, v0
	v_lshl_add_u32 v77, v1, 16, s2
	v_add_u32_e32 v77, 0x2000, v77
	v_cmp_gt_i32_e32 vcc, s0, v77
	s_and_saveexec_b64 s[6:7], vcc
	s_cbranch_execz .LBB0_2406
	s_add_u32 s8, s44, 0x324c1000
	s_addc_u32 s9, s45, 0
	s_add_u32 s10, s44, 0x34541000
	s_addc_u32 s11, s45, 0
	s_add_u32 s12, s44, 0x3d64d000
	s_addc_u32 s13, s45, 0
	s_add_u32 s14, s44, 0x3d84d000
	s_movk_i32 s0, 0x2100
	s_addc_u32 s15, s45, 0
	v_mul_lo_u32 v1, v1, s0
	v_bfe_u32 v3, v0, 4, 2
	v_and_b32_e32 v76, 15, v0
	s_add_u32 s16, s44, 0x3cc4d000
	v_add_u32_e32 v1, 0, v1
	s_addc_u32 s17, s45, 0
	v_lshlrev_b32_e32 v2, 3, v3
	v_mul_u32_u24_e32 v5, 0x210, v76
	s_add_u32 s18, s44, 0x3cccd000
	v_mov_b32_e32 v79, 0
	v_lshlrev_b32_e32 v4, 9, v76
	v_add3_u32 v92, v1, v5, v2
	v_lshlrev_b32_e32 v6, 8, v76
	v_lshlrev_b32_e32 v8, 2, v3
	s_movk_i32 s24, 0x8000
	s_addc_u32 s19, s45, 0
	v_and_b32_e32 v93, 7, v77
	s_mov_b64 s[20:21], 0
	s_mov_b64 s[22:23], 0x7fff
	s_mov_b32 s25, 63
	v_lshlrev_b32_e32 v80, 1, v2
	v_mov_b32_e32 v81, v79
	v_lshlrev_b32_e32 v82, 1, v4
	v_mov_b32_e32 v83, v79
	s_movk_i32 s0, 0x4000
	s_mov_b32 s1, 0xff800000
	s_mov_b32 s3, 0x8000
	s_mov_b32 s4, 0xc000
	s_mov_b32 s5, 0x10000
	s_mov_b32 s28, 0x14000
	s_mov_b32 s29, 0x18000
	s_mov_b32 s30, 0x1c000
	s_mov_b32 s31, 0x20000
	s_mov_b32 s33, 0x24000
	s_mov_b32 s34, 0x28000
	s_mov_b32 s35, 0x2c000
	s_mov_b32 s36, 0x30000
	s_mov_b32 s37, 0x34000
	s_mov_b32 s38, 0x38000
	s_mov_b32 s39, 0x3c000
	v_lshlrev_b32_e32 v84, 1, v8
	v_mov_b32_e32 v85, v79
	v_lshlrev_b32_e32 v86, 1, v6
	v_mov_b32_e32 v87, v79
	v_add_u32_e32 v94, v92, v2
	s_movk_i32 s40, 0x2000
	s_movk_i32 s41, 0x6000
	s_mov_b32 s42, 0xa000
	s_mov_b32 s43, 0xe000
	s_movk_i32 s48, 0x207f
	s_branch .LBB0_2402
